# remaining s_setprio flips (memory-KV GEMM loop) deleted as well
# speedup vs baseline: 1.0075x; 1.0075x over previous
; #define PG8_STAGE(bufoff, gbase, voff) do { _Pragma("unroll") for (int _i = 0; _i < 2; ++_i) \
;     __builtin_amdgcn_global_load_lds((const unsigned*)((const char*)(gbase) + (voff)[_i]), (PG8_LAS unsigned*)(lds + (bufoff) + ldsw + _i * 8192), 16, 0, 0); } while (0)
; #define PG8_LDA(dst, b, h) do { _Pragma("unroll") for (int m = 0; m < 4; ++m) _Pragma("unroll") for (int k = 0; k < 2; ++k) dst[m][k] = *(const PG8_LAS bf16x8*)(lds + PG8_SA(b, h) + aoff + m * 2048 + k * 1024); } while (0)
; #define PG8_LDB(dst, b, h) do { _Pragma("unroll") for (int n = 0; n < 2; ++n) _Pragma("unroll") for (int k = 0; k < 2; ++k) dst[n][k] = *(const PG8_LAS bf16x8*)(lds + PG8_SB(b, h) + boff + n * 2048 + k * 1024); } while (0)
; #define PG8_MMA(ai, bj, At, Bt) do { __builtin_amdgcn_s_setprio(1); _Pragma("unroll") for (int m = 0; m < 4; ++m) _Pragma("unroll") for (int n = 0; n < 2; ++n) _Pragma("unroll") for (int k = 0; k < 2; ++k) \
;     acc[ai][bj][m][n] = __builtin_amdgcn_mfma_f32_16x16x32_bf16(Bt[n][k], At[m][k], acc[ai][bj][m][n], 0, 0, 0); __builtin_amdgcn_s_setprio(0); } while (0)
; #define PG8_WAIT_V(n) asm volatile("s_waitcnt vmcnt(" #n ")" ::: "memory")
; #define PG8_WAIT_L(n) asm volatile("s_waitcnt lgkmcnt(" #n ")" ::: "memory")
; #define PG8_BAR __builtin_amdgcn_s_barrier()
; #define PG8_SCHED __builtin_amdgcn_sched_barrier(0)
; template <class Epi, class Sched>
; DI void gemm_phase(PG8_LAS unsigned char* lds, const Gemm g, const Sched& S, const Epi& E) {
;     ...
;     for (int t = 0; t < nt; t += 2) {
;       const bool last = (t == nt - 2);
;       const char* a1 = cA + (size_t)(t + 1) * kstep;
;       const char* a2 = last ? nA : cA + (size_t)(t + 2) * kstep; const char* b2 = last ? nB : cB + (size_t)(t + 2) * kstep;
;       const char* a3 = a2 + kstep; const char* b3 = b2 + kstep;
;       PG8_LDB(B0, 0, 0); PG8_LDB(B1, 0, 1); PG8_SCHED; PG8_LDA(At, 0, 0); PG8_STAGE(PG8_SA(1, 1), a1 + hstepA, voffA);
;       PG8_WAIT_V(8); PG8_WAIT_L(0); PG8_BAR; PG8_MMA(0, 0, At, B0); PG8_MMA(0, 1, At, B1); PG8_BAR; PG8_SCHED;
;       PG8_LDA(At, 0, 1); PG8_STAGE(PG8_SB(0, 0), b2, voffB); PG8_STAGE(PG8_SB(0, 1), b2 + hstepB, voffB); PG8_STAGE(PG8_SA(0, 0), a2, voffA);
;       PG8_WAIT_V(8); PG8_WAIT_L(0); PG8_BAR; PG8_MMA(1, 0, At, B0); PG8_MMA(1, 1, At, B1); PG8_BAR; PG8_SCHED;
.LBB0_339:
	ds_read_b128 v[142:145], v151
	ds_read_b128 v[156:159], v151 offset:1024
	ds_read_b128 v[160:163], v151 offset:2048
	ds_read_b128 v[164:167], v151 offset:3072
	ds_read_b128 v[168:171], v152
	ds_read_b128 v[172:175], v152 offset:1024
	ds_read_b128 v[176:179], v152 offset:2048
	ds_read_b128 v[180:183], v152 offset:3072
	s_add_u32 s16, s30, 0xfffc0080
	s_addc_u32 s34, s31, -1
	s_cmp_eq_u32 s76, 12
	s_cselect_b32 s37, s5, s34
	s_cselect_b32 s36, s21, s16
	s_cselect_b32 s35, s19, s75
	s_cselect_b32 s34, s29, s74
	v_lshl_add_u64 v[146:147], s[30:31], 0, v[138:139]
	s_add_i32 m0, s67, 0xc000
	ds_read_b128 v[184:187], v150
	ds_read_b128 v[188:191], v150 offset:1024
	ds_read_b128 v[192:195], v150 offset:2048
	ds_read_b128 v[196:199], v150 offset:3072
	ds_read_b128 v[200:203], v150 offset:4096
	ds_read_b128 v[204:207], v150 offset:5120
	ds_read_b128 v[208:211], v150 offset:6144
	ds_read_b128 v[214:217], v150 offset:7168
	global_load_lds_dwordx4 v[146:147], off
	v_lshl_add_u64 v[146:147], s[30:31], 0, v[140:141]
	s_add_i32 m0, s67, 0xe000
	s_nop 0
	global_load_lds_dwordx4 v[146:147], off
	s_waitcnt vmcnt(8)
	s_waitcnt lgkmcnt(0)
	s_barrier
	s_waitcnt lgkmcnt(0)
	v_mfma_f32_16x16x32_bf16 v[126:129], v[142:145], v[184:187], v[126:129]
	v_mfma_f32_16x16x32_bf16 v[122:125], v[160:163], v[184:187], v[122:125]
	v_mfma_f32_16x16x32_bf16 v[114:117], v[142:145], v[192:195], v[114:117]
	v_mfma_f32_16x16x32_bf16 v[106:109], v[160:163], v[192:195], v[106:109]
	v_mfma_f32_16x16x32_bf16 v[98:101], v[142:145], v[200:203], v[98:101]
	v_mfma_f32_16x16x32_bf16 v[90:93], v[160:163], v[200:203], v[90:93]
	v_mfma_f32_16x16x32_bf16 v[82:85], v[142:145], v[208:211], v[82:85]
	v_mfma_f32_16x16x32_bf16 v[74:77], v[160:163], v[208:211], v[74:77]
	v_mfma_f32_16x16x32_bf16 v[126:129], v[156:159], v[188:191], v[126:129]
	v_mfma_f32_16x16x32_bf16 v[122:125], v[164:167], v[188:191], v[122:125]
	v_mfma_f32_16x16x32_bf16 v[114:117], v[156:159], v[196:199], v[114:117]
	v_mfma_f32_16x16x32_bf16 v[106:109], v[164:167], v[196:199], v[106:109]
	v_mfma_f32_16x16x32_bf16 v[98:101], v[156:159], v[204:207], v[98:101]
	v_mfma_f32_16x16x32_bf16 v[90:93], v[164:167], v[204:207], v[90:93]
	v_mfma_f32_16x16x32_bf16 v[82:85], v[156:159], v[214:217], v[82:85]
	v_mfma_f32_16x16x32_bf16 v[74:77], v[164:167], v[214:217], v[74:77]
	v_mfma_f32_16x16x32_bf16 v[118:121], v[168:171], v[184:187], v[118:121]
	v_mfma_f32_16x16x32_bf16 v[110:113], v[176:179], v[184:187], v[110:113]
	v_mfma_f32_16x16x32_bf16 v[102:105], v[168:171], v[192:195], v[102:105]
	v_mfma_f32_16x16x32_bf16 v[94:97], v[176:179], v[192:195], v[94:97]
	v_mfma_f32_16x16x32_bf16 v[86:89], v[168:171], v[200:203], v[86:89]
	v_mfma_f32_16x16x32_bf16 v[78:81], v[176:179], v[200:203], v[78:81]
	v_mfma_f32_16x16x32_bf16 v[70:73], v[168:171], v[208:211], v[70:73]
	v_mfma_f32_16x16x32_bf16 v[66:69], v[176:179], v[208:211], v[66:69]
	v_mfma_f32_16x16x32_bf16 v[118:121], v[172:175], v[188:191], v[118:121]
	v_mfma_f32_16x16x32_bf16 v[110:113], v[180:183], v[188:191], v[110:113]
	v_mfma_f32_16x16x32_bf16 v[102:105], v[172:175], v[196:199], v[102:105]
	v_mfma_f32_16x16x32_bf16 v[94:97], v[180:183], v[196:199], v[94:97]
	v_mfma_f32_16x16x32_bf16 v[86:89], v[172:175], v[204:207], v[86:89]
	v_mfma_f32_16x16x32_bf16 v[78:81], v[180:183], v[204:207], v[78:81]
	v_mfma_f32_16x16x32_bf16 v[70:73], v[172:175], v[214:217], v[70:73]
	v_mfma_f32_16x16x32_bf16 v[66:69], v[180:183], v[214:217], v[66:69]
	s_barrier
	s_add_i32 s16, s39, s66
	v_lshl_add_u64 v[146:147], s[34:35], 0, v[130:131]
	s_mov_b32 m0, s16
	ds_read_b128 v[184:187], v150 offset:16384
	ds_read_b128 v[188:191], v150 offset:17408
	ds_read_b128 v[192:195], v150 offset:18432
	ds_read_b128 v[196:199], v150 offset:19456
	ds_read_b128 v[200:203], v150 offset:20480
	ds_read_b128 v[204:207], v150 offset:21504
	ds_read_b128 v[208:211], v150 offset:22528
	ds_read_b128 v[214:217], v150 offset:23552
	global_load_lds_dwordx4 v[146:147], off
	s_add_i32 m0, s16, 0x2000
	s_add_u32 s56, s34, 0x40000
	v_lshl_add_u64 v[218:219], s[34:35], 0, v[136:137]
	s_addc_u32 s57, s35, 0
	s_add_i32 s16, s40, s66
	global_load_lds_dwordx4 v[218:219], off
	v_lshl_add_u64 v[220:221], s[56:57], 0, v[130:131]
	s_mov_b32 m0, s16
	v_lshl_add_u64 v[222:223], s[36:37], 0, v[134:135]
	global_load_lds_dwordx4 v[220:221], off
	v_lshl_add_u64 v[220:221], s[56:57], 0, v[136:137]
	s_add_i32 m0, s16, 0x2000
	s_nop 0
	global_load_lds_dwordx4 v[220:221], off
	v_lshl_add_u64 v[220:221], s[36:37], 0, v[132:133]
	s_mov_b32 m0, s67
	s_nop 0
	global_load_lds_dwordx4 v[220:221], off
	s_mov_b32 m0, s68
	s_nop 0
	global_load_lds_dwordx4 v[222:223], off
	s_waitcnt vmcnt(8)
	s_waitcnt lgkmcnt(0)
	s_barrier
; #define PG8_STAGE(bufoff, gbase, voff) do { _Pragma("unroll") for (int _i = 0; _i < 2; ++_i) \
;     __builtin_amdgcn_global_load_lds((const unsigned*)((const char*)(gbase) + (voff)[_i]), (PG8_LAS unsigned*)(lds + (bufoff) + ldsw + _i * 8192), 16, 0, 0); } while (0)
; #define PG8_LDA(dst, b, h) do { _Pragma("unroll") for (int m = 0; m < 4; ++m) _Pragma("unroll") for (int k = 0; k < 2; ++k) dst[m][k] = *(const PG8_LAS bf16x8*)(lds + PG8_SA(b, h) + aoff + m * 2048 + k * 1024); } while (0)
; #define PG8_LDB(dst, b, h) do { _Pragma("unroll") for (int n = 0; n < 2; ++n) _Pragma("unroll") for (int k = 0; k < 2; ++k) dst[n][k] = *(const PG8_LAS bf16x8*)(lds + PG8_SB(b, h) + boff + n * 2048 + k * 1024); } while (0)
; #define PG8_MMA(ai, bj, At, Bt) do { __builtin_amdgcn_s_setprio(1); _Pragma("unroll") for (int m = 0; m < 4; ++m) _Pragma("unroll") for (int n = 0; n < 2; ++n) _Pragma("unroll") for (int k = 0; k < 2; ++k) \
;     acc[ai][bj][m][n] = __builtin_amdgcn_mfma_f32_16x16x32_bf16(Bt[n][k], At[m][k], acc[ai][bj][m][n], 0, 0, 0); __builtin_amdgcn_s_setprio(0); } while (0)
; #define PG8_WAIT_V(n) asm volatile("s_waitcnt vmcnt(" #n ")" ::: "memory")
; #define PG8_WAIT_L(n) asm volatile("s_waitcnt lgkmcnt(" #n ")" ::: "memory")
; #define PG8_BAR __builtin_amdgcn_s_barrier()
; #define PG8_SCHED __builtin_amdgcn_sched_barrier(0)
; template <class Epi, class Sched>
; DI void gemm_phase(PG8_LAS unsigned char* lds, const Gemm g, const Sched& S, const Epi& E) {
;     ...
;       PG8_WAIT_V(8); PG8_WAIT_L(0); PG8_BAR; PG8_MMA(1, 0, At, B0); PG8_MMA(1, 1, At, B1); PG8_BAR; PG8_SCHED;
;       PG8_LDB(B0, 1, 0); PG8_LDB(B1, 1, 1); PG8_SCHED; PG8_LDA(At, 1, 0); PG8_STAGE(PG8_SA(0, 1), a2 + hstepA, voffA);
;       PG8_WAIT_V(8); PG8_WAIT_L(0); PG8_BAR; PG8_MMA(0, 0, At, B0); PG8_MMA(0, 1, At, B1); PG8_BAR; PG8_SCHED;
	s_waitcnt lgkmcnt(0)
	v_mfma_f32_16x16x32_bf16 v[62:65], v[142:145], v[184:187], v[62:65]
	v_mfma_f32_16x16x32_bf16 v[58:61], v[160:163], v[184:187], v[58:61]
	v_mfma_f32_16x16x32_bf16 v[50:53], v[142:145], v[192:195], v[50:53]
	v_mfma_f32_16x16x32_bf16 v[42:45], v[160:163], v[192:195], v[42:45]
	v_mfma_f32_16x16x32_bf16 v[34:37], v[142:145], v[200:203], v[34:37]
	v_mfma_f32_16x16x32_bf16 v[26:29], v[160:163], v[200:203], v[26:29]
	v_mfma_f32_16x16x32_bf16 v[18:21], v[142:145], v[208:211], v[18:21]
	v_mfma_f32_16x16x32_bf16 v[10:13], v[160:163], v[208:211], v[10:13]
	v_mfma_f32_16x16x32_bf16 v[62:65], v[156:159], v[188:191], v[62:65]
	v_mfma_f32_16x16x32_bf16 v[58:61], v[164:167], v[188:191], v[58:61]
	v_mfma_f32_16x16x32_bf16 v[50:53], v[156:159], v[196:199], v[50:53]
	v_mfma_f32_16x16x32_bf16 v[42:45], v[164:167], v[196:199], v[42:45]
	v_mfma_f32_16x16x32_bf16 v[34:37], v[156:159], v[204:207], v[34:37]
	v_mfma_f32_16x16x32_bf16 v[26:29], v[164:167], v[204:207], v[26:29]
	v_mfma_f32_16x16x32_bf16 v[18:21], v[156:159], v[214:217], v[18:21]
	v_mfma_f32_16x16x32_bf16 v[10:13], v[164:167], v[214:217], v[10:13]
	v_mfma_f32_16x16x32_bf16 v[54:57], v[168:171], v[184:187], v[54:57]
	v_mfma_f32_16x16x32_bf16 v[46:49], v[176:179], v[184:187], v[46:49]
	v_mfma_f32_16x16x32_bf16 v[38:41], v[168:171], v[192:195], v[38:41]
	v_mfma_f32_16x16x32_bf16 v[30:33], v[176:179], v[192:195], v[30:33]
	v_mfma_f32_16x16x32_bf16 v[22:25], v[168:171], v[200:203], v[22:25]
	v_mfma_f32_16x16x32_bf16 v[14:17], v[176:179], v[200:203], v[14:17]
	v_mfma_f32_16x16x32_bf16 v[6:9], v[168:171], v[208:211], v[6:9]
	v_mfma_f32_16x16x32_bf16 v[2:5], v[176:179], v[208:211], v[2:5]
	v_mfma_f32_16x16x32_bf16 v[54:57], v[172:175], v[188:191], v[54:57]
	v_mfma_f32_16x16x32_bf16 v[46:49], v[180:183], v[188:191], v[46:49]
	v_mfma_f32_16x16x32_bf16 v[38:41], v[172:175], v[196:199], v[38:41]
	v_mfma_f32_16x16x32_bf16 v[30:33], v[180:183], v[196:199], v[30:33]
	v_mfma_f32_16x16x32_bf16 v[22:25], v[172:175], v[204:207], v[22:25]
	v_mfma_f32_16x16x32_bf16 v[14:17], v[180:183], v[204:207], v[14:17]
	v_mfma_f32_16x16x32_bf16 v[6:9], v[172:175], v[214:217], v[6:9]
	v_mfma_f32_16x16x32_bf16 v[2:5], v[180:183], v[214:217], v[2:5]
	s_barrier
	ds_read_b128 v[142:145], v153
	ds_read_b128 v[156:159], v153 offset:1024
	ds_read_b128 v[160:163], v153 offset:2048
	ds_read_b128 v[164:167], v153 offset:3072
	ds_read_b128 v[168:171], v154
	ds_read_b128 v[172:175], v154 offset:1024
	ds_read_b128 v[176:179], v154 offset:2048
	ds_read_b128 v[180:183], v154 offset:3072
	s_add_u32 s36, s36, 0x40000
	s_addc_u32 s37, s37, 0
	s_mov_b32 m0, s69
	v_lshl_add_u64 v[224:225], s[36:37], 0, v[132:133]
	ds_read_b128 v[184:187], v150 offset:32768
	ds_read_b128 v[188:191], v150 offset:33792
	ds_read_b128 v[192:195], v150 offset:34816
	ds_read_b128 v[196:199], v150 offset:35840
	ds_read_b128 v[200:203], v150 offset:36864
	ds_read_b128 v[204:207], v150 offset:37888
	ds_read_b128 v[208:211], v150 offset:38912
	ds_read_b128 v[214:217], v150 offset:39936
	global_load_lds_dwordx4 v[224:225], off
	v_lshl_add_u64 v[224:225], s[36:37], 0, v[134:135]
	s_mov_b32 m0, s70
	s_nop 0
	global_load_lds_dwordx4 v[224:225], off
	s_waitcnt vmcnt(8)
	s_waitcnt lgkmcnt(0)
	s_barrier
	s_waitcnt lgkmcnt(0)
	v_mfma_f32_16x16x32_bf16 v[126:129], v[142:145], v[184:187], v[126:129]
	v_mfma_f32_16x16x32_bf16 v[122:125], v[160:163], v[184:187], v[122:125]
	v_mfma_f32_16x16x32_bf16 v[114:117], v[142:145], v[192:195], v[114:117]
	v_mfma_f32_16x16x32_bf16 v[106:109], v[160:163], v[192:195], v[106:109]
	v_mfma_f32_16x16x32_bf16 v[98:101], v[142:145], v[200:203], v[98:101]
	v_mfma_f32_16x16x32_bf16 v[90:93], v[160:163], v[200:203], v[90:93]
	v_mfma_f32_16x16x32_bf16 v[82:85], v[142:145], v[208:211], v[82:85]
	v_mfma_f32_16x16x32_bf16 v[74:77], v[160:163], v[208:211], v[74:77]
	v_mfma_f32_16x16x32_bf16 v[126:129], v[156:159], v[188:191], v[126:129]
	v_mfma_f32_16x16x32_bf16 v[122:125], v[164:167], v[188:191], v[122:125]
	v_mfma_f32_16x16x32_bf16 v[114:117], v[156:159], v[196:199], v[114:117]
	v_mfma_f32_16x16x32_bf16 v[106:109], v[164:167], v[196:199], v[106:109]
	v_mfma_f32_16x16x32_bf16 v[98:101], v[156:159], v[204:207], v[98:101]
	v_mfma_f32_16x16x32_bf16 v[90:93], v[164:167], v[204:207], v[90:93]
	v_mfma_f32_16x16x32_bf16 v[82:85], v[156:159], v[214:217], v[82:85]
	v_mfma_f32_16x16x32_bf16 v[74:77], v[164:167], v[214:217], v[74:77]
	v_mfma_f32_16x16x32_bf16 v[118:121], v[168:171], v[184:187], v[118:121]
	v_mfma_f32_16x16x32_bf16 v[110:113], v[176:179], v[184:187], v[110:113]
	v_mfma_f32_16x16x32_bf16 v[102:105], v[168:171], v[192:195], v[102:105]
	v_mfma_f32_16x16x32_bf16 v[94:97], v[176:179], v[192:195], v[94:97]
	v_mfma_f32_16x16x32_bf16 v[86:89], v[168:171], v[200:203], v[86:89]
	v_mfma_f32_16x16x32_bf16 v[78:81], v[176:179], v[200:203], v[78:81]
	v_mfma_f32_16x16x32_bf16 v[70:73], v[168:171], v[208:211], v[70:73]
	v_mfma_f32_16x16x32_bf16 v[66:69], v[176:179], v[208:211], v[66:69]
	v_mfma_f32_16x16x32_bf16 v[118:121], v[172:175], v[188:191], v[118:121]
	v_mfma_f32_16x16x32_bf16 v[110:113], v[180:183], v[188:191], v[110:113]
	v_mfma_f32_16x16x32_bf16 v[102:105], v[172:175], v[196:199], v[102:105]
	v_mfma_f32_16x16x32_bf16 v[94:97], v[180:183], v[196:199], v[94:97]
	v_mfma_f32_16x16x32_bf16 v[86:89], v[172:175], v[204:207], v[86:89]
	v_mfma_f32_16x16x32_bf16 v[78:81], v[180:183], v[204:207], v[78:81]
	v_mfma_f32_16x16x32_bf16 v[70:73], v[172:175], v[214:217], v[70:73]
	v_mfma_f32_16x16x32_bf16 v[66:69], v[180:183], v[214:217], v[66:69]
	s_barrier
; #define PG8_STAGE(bufoff, gbase, voff) do { _Pragma("unroll") for (int _i = 0; _i < 2; ++_i) \
;     __builtin_amdgcn_global_load_lds((const unsigned*)((const char*)(gbase) + (voff)[_i]), (PG8_LAS unsigned*)(lds + (bufoff) + ldsw + _i * 8192), 16, 0, 0); } while (0)
; #define PG8_LDA(dst, b, h) do { _Pragma("unroll") for (int m = 0; m < 4; ++m) _Pragma("unroll") for (int k = 0; k < 2; ++k) dst[m][k] = *(const PG8_LAS bf16x8*)(lds + PG8_SA(b, h) + aoff + m * 2048 + k * 1024); } while (0)
; #define PG8_MMA(ai, bj, At, Bt) do { __builtin_amdgcn_s_setprio(1); _Pragma("unroll") for (int m = 0; m < 4; ++m) _Pragma("unroll") for (int n = 0; n < 2; ++n) _Pragma("unroll") for (int k = 0; k < 2; ++k) \
;     acc[ai][bj][m][n] = __builtin_amdgcn_mfma_f32_16x16x32_bf16(Bt[n][k], At[m][k], acc[ai][bj][m][n], 0, 0, 0); __builtin_amdgcn_s_setprio(0); } while (0)
; #define PG8_WAIT_V(n) asm volatile("s_waitcnt vmcnt(" #n ")" ::: "memory")
; #define PG8_WAIT_L(n) asm volatile("s_waitcnt lgkmcnt(" #n ")" ::: "memory")
; #define PG8_BAR __builtin_amdgcn_s_barrier()
; #define PG8_SCHED __builtin_amdgcn_sched_barrier(0)
; template <class Epi, class Sched>
; DI void gemm_phase(PG8_LAS unsigned char* lds, const Gemm g, const Sched& S, const Epi& E) {
;     ...
;       PG8_LDA(At, 1, 1); PG8_STAGE(PG8_SB(1, 0), b3, voffB); PG8_STAGE(PG8_SB(1, 1), b3 + hstepB, voffB); PG8_STAGE(PG8_SA(1, 0), a3, voffA);
;       PG8_WAIT_V(8); PG8_WAIT_L(0); PG8_BAR; PG8_MMA(1, 0, At, B0); PG8_MMA(1, 1, At, B1); PG8_BAR; PG8_SCHED;
;     }
;     if (wr == 0) PG8_BAR;
	s_add_i32 s16, s41, s66
	v_lshl_add_u64 v[146:147], v[146:147], 0, s[6:7]
	s_mov_b32 m0, s16
	ds_read_b128 v[184:187], v150 offset:49152
	ds_read_b128 v[188:191], v150 offset:50176
	ds_read_b128 v[192:195], v150 offset:51200
	ds_read_b128 v[196:199], v150 offset:52224
	ds_read_b128 v[200:203], v150 offset:53248
	ds_read_b128 v[204:207], v150 offset:54272
	ds_read_b128 v[208:211], v150 offset:55296
	ds_read_b128 v[214:217], v150 offset:56320
	global_load_lds_dwordx4 v[146:147], off
	s_add_i32 m0, s16, 0x2000
	s_add_u32 s34, s34, 0x40080
	v_lshl_add_u64 v[146:147], v[218:219], 0, s[6:7]
	s_addc_u32 s35, s35, 0
	s_add_i32 s16, s53, s66
	global_load_lds_dwordx4 v[146:147], off
	v_lshl_add_u64 v[146:147], s[34:35], 0, v[130:131]
	s_mov_b32 m0, s16
	s_nop 0
	global_load_lds_dwordx4 v[146:147], off
	v_lshl_add_u64 v[146:147], s[34:35], 0, v[136:137]
	s_add_i32 m0, s16, 0x2000
	s_nop 0
	global_load_lds_dwordx4 v[146:147], off
	v_lshl_add_u64 v[146:147], v[220:221], 0, s[6:7]
	s_mov_b32 m0, s71
	s_nop 0
	global_load_lds_dwordx4 v[146:147], off
	v_lshl_add_u64 v[146:147], v[222:223], 0, s[6:7]
	s_mov_b32 m0, s72
	s_nop 0
	global_load_lds_dwordx4 v[146:147], off
	s_waitcnt vmcnt(8)
	s_waitcnt lgkmcnt(0)
	s_barrier
	s_waitcnt lgkmcnt(0)
	v_mfma_f32_16x16x32_bf16 v[62:65], v[142:145], v[184:187], v[62:65]
	v_mfma_f32_16x16x32_bf16 v[58:61], v[160:163], v[184:187], v[58:61]
	v_mfma_f32_16x16x32_bf16 v[50:53], v[142:145], v[192:195], v[50:53]
	v_mfma_f32_16x16x32_bf16 v[42:45], v[160:163], v[192:195], v[42:45]
	v_mfma_f32_16x16x32_bf16 v[34:37], v[142:145], v[200:203], v[34:37]
	v_mfma_f32_16x16x32_bf16 v[26:29], v[160:163], v[200:203], v[26:29]
	v_mfma_f32_16x16x32_bf16 v[18:21], v[142:145], v[208:211], v[18:21]
	v_mfma_f32_16x16x32_bf16 v[10:13], v[160:163], v[208:211], v[10:13]
	v_mfma_f32_16x16x32_bf16 v[62:65], v[156:159], v[188:191], v[62:65]
	v_mfma_f32_16x16x32_bf16 v[58:61], v[164:167], v[188:191], v[58:61]
	v_mfma_f32_16x16x32_bf16 v[50:53], v[156:159], v[196:199], v[50:53]
	v_mfma_f32_16x16x32_bf16 v[42:45], v[164:167], v[196:199], v[42:45]
	v_mfma_f32_16x16x32_bf16 v[34:37], v[156:159], v[204:207], v[34:37]
	v_mfma_f32_16x16x32_bf16 v[26:29], v[164:167], v[204:207], v[26:29]
	v_mfma_f32_16x16x32_bf16 v[18:21], v[156:159], v[214:217], v[18:21]
	v_mfma_f32_16x16x32_bf16 v[10:13], v[164:167], v[214:217], v[10:13]
	v_mfma_f32_16x16x32_bf16 v[54:57], v[168:171], v[184:187], v[54:57]
	v_mfma_f32_16x16x32_bf16 v[46:49], v[176:179], v[184:187], v[46:49]
	v_mfma_f32_16x16x32_bf16 v[38:41], v[168:171], v[192:195], v[38:41]
	v_mfma_f32_16x16x32_bf16 v[30:33], v[176:179], v[192:195], v[30:33]
	v_mfma_f32_16x16x32_bf16 v[22:25], v[168:171], v[200:203], v[22:25]
	v_mfma_f32_16x16x32_bf16 v[14:17], v[176:179], v[200:203], v[14:17]
	v_mfma_f32_16x16x32_bf16 v[6:9], v[168:171], v[208:211], v[6:9]
	v_mfma_f32_16x16x32_bf16 v[2:5], v[176:179], v[208:211], v[2:5]
	v_mfma_f32_16x16x32_bf16 v[54:57], v[172:175], v[188:191], v[54:57]
	v_mfma_f32_16x16x32_bf16 v[46:49], v[180:183], v[188:191], v[46:49]
	v_mfma_f32_16x16x32_bf16 v[38:41], v[172:175], v[196:199], v[38:41]
	v_mfma_f32_16x16x32_bf16 v[30:33], v[180:183], v[196:199], v[30:33]
	v_mfma_f32_16x16x32_bf16 v[22:25], v[172:175], v[204:207], v[22:25]
	v_mfma_f32_16x16x32_bf16 v[14:17], v[180:183], v[204:207], v[14:17]
	v_mfma_f32_16x16x32_bf16 v[6:9], v[172:175], v[214:217], v[6:9]
	v_mfma_f32_16x16x32_bf16 v[2:5], v[180:183], v[214:217], v[2:5]
	s_barrier
	s_add_i32 s76, s76, 2
	s_add_u32 s30, s30, 0x100
	s_addc_u32 s31, s31, 0
	s_add_u32 s74, s74, 0x100
	s_addc_u32 s75, s75, 0
	s_cmp_gt_u32 s76, 13
	s_cbranch_scc0 .LBB0_339
	s_and_b64 vcc, exec, s[14:15]
	s_cbranch_vccz .LBB0_342
	s_barrier
